# one static s_setprio 1 for waves 4-7 across the attention phase (on top of the no-flips GEMM loops)
# speedup vs baseline: 1.0049x; 1.0026x over previous
.LBB0_503:
	v_readlane_b32 s0, v255, 0
	s_cmpk_gt_i32 s0, 0x1ff
	s_cbranch_scc1 .LBB0_564
	s_cmpk_gt_u32 s33, 0xff
	s_cbranch_scc0 .Lattn_prio_done
	s_setprio 1
.Lattn_prio_done:
	s_add_u32 s60, s30, 0x15400400
	s_addc_u32 s61, s31, 0
	s_add_u32 s62, s30, 0xb400000
	s_mov_b32 s38, 0xffff0000
	s_addc_u32 s63, s31, 0
	s_mov_b32 s1, 0
	v_mov_b32_e32 v223, 0
	s_mov_b64 s[6:7], 0x10000
	s_mov_b64 s[22:23], 0x20000
	s_mov_b64 s[24:25], 0x30000
	s_mov_b64 s[36:37], 0x50000
	s_add_i32 s64, 0, 0x14900
	s_mov_b32 s39, -1
	s_mov_b64 s[40:41], 0x40000
	v_mov_b32_e32 v233, 0xff800000
	v_readlane_b32 s0, v255, 0
	s_mov_b32 s65, 0
	s_mov_b32 s67, 0
	v_mbcnt_lo_u32_b32 v252, -1, 0
	v_mbcnt_hi_u32_b32 v252, -1, v252
	v_and_b32_e32 v253, 63, v252
	v_and_b32_e32 v254, 31, v252
	v_bfe_u32 v232, v252, 5, 1
	s_lshr_b32 s71, s67, 1
	s_mul_i32 s71, s71, s84
	v_readlane_b32 s72, v255, 0
	s_mov_b64 s[100:101], 0
	s_add_i32 s71, s71, s72
	s_cmpk_lt_i32 s71, 0x200
	s_cbranch_scc0 .Lattn_pf_done_f
	s_ashr_i32 s72, s71, 2
	s_lshl_b32 s73, s71, 8
	s_and_b32 s73, s73, 0x300
	s_and_b32 s74, s67, 1
	s_xor_b32 s75, s73, 0x700
	s_cmp_eq_u32 s74, 0
	s_cselect_b32 s73, s75, s73
	s_add_i32 s74, s73, 0x100
	v_add_u32_e32 v50, s33, v252
	v_lshlrev_b32_e32 v51, 2, v50
	v_lshlrev_b32_e32 v52, 4, v50
	v_cmp_gt_i32_e32 vcc, s74, v51
	s_lshl_b32 s75, s72, 13
	s_add_u32 s80, s18, s75
	s_addc_u32 s81, s19, 0
	s_and_saveexec_b64 s[76:77], vcc
	s_mov_b64 s[100:101], exec
	global_load_dwordx4 v[100:103], v52, s[80:81]
	v_add_u32_e32 v104, 0x14800, v52
	s_mov_b64 exec, s[76:77]
	s_lshr_b32 s54, s72, 3
	s_and_b32 s55, s72, 7
	s_lshl_b32 s75, s54, 11
	s_or_b32 s75, s75, s73
	s_lshr_b32 s81, s33, 1
	s_add_i32 s75, s75, s81
	s_lshl_b32 s75, s75, 10
	s_lshl_b32 s80, s55, 7
	s_add_i32 s75, s75, s80
	s_add_u32 s80, s3, s75
	s_addc_u32 s81, s66, 0
	v_lshlrev_b32_e32 v50, 10, v254
	v_lshl_or_b32 v50, v232, 4, v50
	global_load_dwordx4 v[140:143], v50, s[80:81] nt
	global_load_dwordx4 v[136:139], v50, s[80:81] offset:32 nt
	global_load_dwordx4 v[132:135], v50, s[80:81] offset:64 nt
	global_load_dwordx4 v[128:131], v50, s[80:81] offset:96 nt
	s_lshl_b32 s56, s54, 21
	s_lshl_b32 s57, s55, 7
	s_add_i32 s56, s56, s57
	s_add_u32 s82, s62, s56
	s_addc_u32 s83, s63, 0
	s_add_u32 s94, s20, s56
	s_addc_u32 s95, s21, 0
	s_add_u32 s88, s82, 0x10000
	s_addc_u32 s89, s83, 0
	s_add_u32 s92, s82, 0x20000
	s_addc_u32 s93, s83, 0
	s_lshr_b32 s57, s33, 2
	v_lshl_add_u32 v53, v253, 10, s57
	s_and_b32 s59, s57, 48
	v_bfe_u32 v54, v252, 2, 4
	v_or_b32_e32 v54, s59, v54
	s_lshr_b32 s59, s33, 8
	v_and_b32_e32 v55, 3, v252
	s_lshl_b32 s59, s59, 6
	v_lshlrev_b32_e32 v55, 4, v55
	v_lshl_add_u32 v54, v54, 10, s59
	s_lshl_b32 s32, s33, 4
	v_add_u32_e32 v54, v54, v55
	s_mov_b32 s27, m0
	s_mov_b32 m0, s32
	s_nop 0
	global_load_lds_dwordx4 v53, s[82:83]
	s_add_i32 m0, s32, 0x6000
	s_nop 0
	global_load_lds_dwordx4 v54, s[94:95]
	s_add_i32 m0, s32, 0x2000
	s_nop 0
	global_load_lds_dwordx4 v53, s[88:89]
	s_add_i32 m0, s32, 0x4000
	s_nop 0
	global_load_lds_dwordx4 v53, s[92:93]
	s_mov_b32 m0, s27

.LBB0_564:
	s_setprio 0
	s_waitcnt vmcnt(0)
	s_barrier
	s_mov_b64 s[0:1], exec
	v_readlane_b32 s4, v255, 21
	v_readlane_b32 s5, v255, 22
	s_and_b64 s[4:5], s[0:1], s[4:5]
	s_mov_b64 exec, s[4:5]
	s_cbranch_execz .LBB0_616
	s_add_i32 s3, 0, 0x20160
	v_mov_b32_e32 v0, s3
	s_waitcnt vmcnt(0) expcnt(0) lgkmcnt(0)
	ds_read_b32 v2, v0
	s_add_i32 s3, 0, 0x20164
	v_mov_b32_e32 v0, s3
	ds_read_b32 v0, v0
	s_waitcnt lgkmcnt(1)
	v_cmp_ne_u32_e32 vcc, 0, v2
	s_cbranch_vccnz .LBB0_580
	s_add_u32 s4, s30, 0x4a0200
	s_addc_u32 s5, s31, 0
	s_add_u32 s6, s30, 0x4a0400
	s_addc_u32 s7, s31, 0
	s_add_u32 s20, s30, 0x4a0500
	s_addc_u32 s21, s31, 0
	s_add_u32 s22, s30, 0x4a0600
	s_addc_u32 s23, s31, 0
	s_add_u32 s24, s30, 0x4a0700
	s_addc_u32 s25, s31, 0
	s_add_u32 s36, s30, 0x4a0800
	s_addc_u32 s37, s31, 0
	s_add_u32 s38, s30, 0x4a0900
	s_addc_u32 s39, s31, 0
	s_add_u32 s40, s30, 0x4a0a00
	s_addc_u32 s41, s31, 0
	s_add_u32 s42, s30, 0x4a0b00
	s_addc_u32 s43, s31, 0
	s_add_u32 s44, s30, 0x4a0c00
	s_addc_u32 s45, s31, 0
	s_add_u32 s50, s30, 0x4a0d00
	s_addc_u32 s51, s31, 0
	s_add_u32 s52, s30, 0x4a0e00
	s_addc_u32 s53, s31, 0
	s_add_u32 s56, s30, 0x4a0f00
	s_addc_u32 s57, s31, 0
	s_add_u32 s58, s30, 0x4a1000
	s_addc_u32 s59, s31, 0
	s_add_u32 s60, s30, 0x4a1100
	s_addc_u32 s61, s31, 0
	s_add_u32 s62, s30, 0x4a1200
	v_readlane_b32 s3, v255, 1
	s_addc_u32 s63, s31, 0
	s_mul_i32 s3, s85, s3
	s_add_u32 s64, s30, 0x4a1300
	s_mul_i32 s3, s3, s84
	s_addc_u32 s65, s31, 0
	s_mov_b32 s72, 1
	v_mov_b32_e32 v16, 0
	s_branch .LBB0_568
